# static s_setprio 1 for waves 4-7 during the attention units (strategy: one static priority raise for the younger half)
# speedup vs baseline: 1.0026x; 1.0026x over previous
.LBB0_385:
	s_cmp_lt_u32 s28, 4
	s_cbranch_scc1 .Lprio_done
	s_setprio 1

.LBB0_476:
	s_setprio 0
	s_ashr_i32 s4, s3, 31
	s_lshr_b32 s4, s4, 29
	s_add_i32 s4, s3, s4
	v_lshlrev_b32_e32 v1, 6, v0
	s_ashr_i32 s4, s4, 3
	v_and_b32_e32 v149, 0x3c0, v1
	v_lshlrev_b32_e32 v1, 2, v0
	s_mul_i32 s20, s4, s66
	v_and_b32_e32 v147, 32, v1
	v_lshrrev_b32_e32 v1, 5, v0
	v_lshrrev_b32_e32 v3, 1, v0
	s_add_i32 s20, s20, s67
	v_and_b32_e32 v1, 4, v1
	v_bfe_u32 v2, v0, 2, 2
	v_and_b32_e32 v142, 24, v3
	s_and_b32 s22, s20, 3
	v_or3_b32 v1, v1, v2, v142
	v_lshlrev_b32_e32 v2, 4, v0
	s_bitcmp0_b32 s20, 2
	v_or_b32_e32 v145, 0x2000, v2
	s_cselect_b64 s[4:5], -1, 0
	v_lshrrev_b32_e32 v3, 7, v145
	s_movk_i32 s6, 0x60
	v_and_b32_e32 v4, 32, v0
	s_and_b64 s[4:5], s[8:9], s[4:5]
	v_and_or_b32 v150, v3, s6, v1
	v_bitop3_b32 v143, v2, v4, 48 bitop3:0x6c
	v_and_b32_e32 v144, 64, v0
	v_bfe_u32 v146, v0, 2, 4
	s_movk_i32 s6, 0x70
	v_lshrrev_b32_e32 v2, 3, v0
	v_and_b32_e32 v148, 15, v0
	v_or_b32_e32 v151, v143, v144
	v_and_or_b32 v152, v3, s6, v146
	v_and_or_b32 v153, v2, 32, v1
	v_and_or_b32 v154, v2, 48, v146
	s_mov_b64 s[6:7], s[24:25]
	s_andn2_b64 vcc, exec, s[4:5]
	s_mov_b64 s[4:5], -1
	s_cbranch_vccz .LBB0_494
	s_andn2_b64 vcc, exec, s[8:9]
	s_cbranch_vccnz .LBB0_493
	s_ashr_i32 s21, s20, 1
	s_cmpk_gt_u32 s21, 0x7f
	v_readfirstlane_b32 s23, v0
	s_cbranch_scc1 .LBB0_486
	s_lshr_b32 s11, s23, 6
	s_or_b32 s34, s22, 12
	s_lshr_b32 s35, s21, 2
	s_lshr_b32 s10, s23, 8
	s_lshl_b32 s16, s11, 10
	s_lshl_b32 s12, s35, 20
	s_lshl_b32 s4, s34, 20
	s_add_u32 s8, s6, s4
	s_addc_u32 s9, s7, 0
	s_add_u32 s4, s8, 0x200000
	s_addc_u32 s5, s9, 0
	s_add_i32 s36, s16, 0
	v_lshl_or_b32 v134, v153, 12, v151
	s_add_i32 m0, s36, 0x10000
	v_lshl_or_b32 v130, v150, 12, v151
	global_load_lds_dwordx4 v134, s[4:5]
	s_add_i32 m0, s36, 0x12000
	s_add_u32 s8, s8, 0x280000
	global_load_lds_dwordx4 v130, s[4:5]
	s_addc_u32 s9, s9, 0
	s_add_i32 m0, s36, 0x14000
	v_lshl_or_b32 v136, v154, 12, v151
	global_load_lds_dwordx4 v134, s[8:9]
	s_add_i32 m0, s36, 0x16000
	s_add_u32 s13, s6, s12
	s_addc_u32 s15, s7, 0
	global_load_lds_dwordx4 v130, s[8:9]
	s_add_u32 s8, s13, 0x3000000
	s_addc_u32 s9, s15, 0
	s_add_i32 s37, s36, 0x2000
	s_mov_b32 m0, s36
	s_add_u32 s14, s13, 0x3080000
	v_lshl_or_b32 v132, v152, 12, v151
	global_load_lds_dwordx4 v136, s[8:9]
	s_mov_b32 m0, s37
	s_addc_u32 s15, s15, 0
	s_add_i32 s38, s36, 0x4000
	global_load_lds_dwordx4 v132, s[8:9]
	s_mov_b32 m0, s38
	s_add_i32 s39, s36, 0x6000
	global_load_lds_dwordx4 v136, s[14:15]
	s_mov_b32 m0, s39
	v_mov_b32_e32 v135, 0
	global_load_lds_dwordx4 v132, s[14:15]
	v_mov_b32_e32 v131, v135
	v_mov_b32_e32 v137, v135
	v_mov_b32_e32 v133, v135
	v_lshl_add_u64 v[8:9], s[4:5], 0, v[134:135]
	v_lshl_add_u64 v[6:7], s[4:5], 0, v[130:131]
	v_lshl_add_u64 v[4:5], s[8:9], 0, v[136:137]
	s_cmp_lg_u32 s10, 1
	v_lshl_add_u64 v[2:3], s[8:9], 0, v[132:133]
	s_cbranch_scc1 .LBB0_481
	s_barrier
